# grid barrier: XCD leader bumps the per-XCD generation before (not after) its own acquire-invalidate; followers acquire themselves
# baseline (speedup 1.0000x reference)
; __device__ __forceinline__ unsigned xb_ld(unsigned* p)              { return __hip_atomic_load(p, __ATOMIC_RELAXED, __HIP_MEMORY_SCOPE_AGENT); }
; __device__ __forceinline__ unsigned xb_add(unsigned* p, unsigned v) { return __hip_atomic_fetch_add(p, v, __ATOMIC_RELAXED, __HIP_MEMORY_SCOPE_AGENT); }
; #define XB_SPIN(cond, bar) do { unsigned _sp = 0; while (cond) { __builtin_amdgcn_s_sleep(1); \
;     if ((++_sp & 255u) == 0u) { if (xb_ld(&(bar)[XB_TMO])) break; if (_sp > XB_SPIN_CAP) { atomicAdd(&(bar)[XB_TMO], 1u); break; } } } } while (0)
; __device__ __forceinline__ void xcd_barrier(const XcdBarrier& b) {
;     ...
;             const unsigned og = xb_add(&bar[XB_TOP], 1u);
;             const unsigned tg = og / nx;
;             if (og + 1u == (tg + 1u) * nx) xb_add(&bar[XB_TOPGEN], 1u);
;             else XB_SPIN(xb_ld(&bar[XB_TOPGEN]) == tg, bar);
;             __builtin_amdgcn_fence(__ATOMIC_ACQUIRE, "agent");
;             xb_add(&bar[XB_XGEN(b.x)], 1u);
;             asm volatile("s_waitcnt vmcnt(0)" ::: "memory");
;         } else {
;             XB_SPIN(xb_ld(&bar[XB_XGEN(b.x)]) == gen, bar);
;             __builtin_amdgcn_fence(__ATOMIC_ACQUIRE, "agent");
;             asm volatile("s_waitcnt vmcnt(0)" ::: "memory");
.LBB0_95:
	s_or_b64 exec, exec, s[14:15]
	s_mov_b64 s[14:15], exec
	v_mbcnt_lo_u32_b32 v1, s14, 0
	v_mbcnt_hi_u32_b32 v1, s15, v1
	v_cmp_eq_u32_e32 vcc, 0, v1
	s_waitcnt vmcnt(0)
	s_and_saveexec_b64 s[16:17], vcc
	s_cbranch_execz .LBB0_97
	s_bcnt1_i32_b64 s6, s[14:15]
	v_mov_b32_e32 v1, 0x2000
	v_mov_b32_e32 v2, s6
	global_atomic_add v1, v2, s[10:11] offset:1024
.LBB0_97:
	s_or_b64 exec, exec, s[16:17]
	buffer_inv sc1
	s_waitcnt vmcnt(0)

; __device__ __forceinline__ unsigned xb_ld(unsigned* p)              { return __hip_atomic_load(p, __ATOMIC_RELAXED, __HIP_MEMORY_SCOPE_AGENT); }
; __device__ __forceinline__ unsigned xb_add(unsigned* p, unsigned v) { return __hip_atomic_fetch_add(p, v, __ATOMIC_RELAXED, __HIP_MEMORY_SCOPE_AGENT); }
; #define XB_SPIN(cond, bar) do { unsigned _sp = 0; while (cond) { __builtin_amdgcn_s_sleep(1); \
;     if ((++_sp & 255u) == 0u) { if (xb_ld(&(bar)[XB_TMO])) break; if (_sp > XB_SPIN_CAP) { atomicAdd(&(bar)[XB_TMO], 1u); break; } } } } while (0)
; __device__ __forceinline__ void xcd_barrier(const XcdBarrier& b) {
;     ...
;             const unsigned og = xb_add(&bar[XB_TOP], 1u);
;             const unsigned tg = og / nx;
;             if (og + 1u == (tg + 1u) * nx) xb_add(&bar[XB_TOPGEN], 1u);
;             else XB_SPIN(xb_ld(&bar[XB_TOPGEN]) == tg, bar);
;             __builtin_amdgcn_fence(__ATOMIC_ACQUIRE, "agent");
;             xb_add(&bar[XB_XGEN(b.x)], 1u);
;             asm volatile("s_waitcnt vmcnt(0)" ::: "memory");
;         } else {
;             XB_SPIN(xb_ld(&bar[XB_XGEN(b.x)]) == gen, bar);
;             __builtin_amdgcn_fence(__ATOMIC_ACQUIRE, "agent");
;             asm volatile("s_waitcnt vmcnt(0)" ::: "memory");
.LBB0_214:
	s_or_b64 exec, exec, s[12:13]
	s_mov_b64 s[12:13], exec
	v_mbcnt_lo_u32_b32 v0, s12, 0
	v_mbcnt_hi_u32_b32 v0, s13, v0
	v_cmp_eq_u32_e32 vcc, 0, v0
	s_waitcnt vmcnt(0)
	s_and_saveexec_b64 s[14:15], vcc
	s_cbranch_execz .LBB0_216
	s_bcnt1_i32_b64 s6, s[12:13]
	v_mov_b32_e32 v0, 0x2000
	v_mov_b32_e32 v1, s6
	global_atomic_add v0, v1, s[10:11] offset:1024
.LBB0_216:
	s_or_b64 exec, exec, s[14:15]
	buffer_inv sc1
	s_waitcnt vmcnt(0)

; __device__ __forceinline__ unsigned xb_ld(unsigned* p)              { return __hip_atomic_load(p, __ATOMIC_RELAXED, __HIP_MEMORY_SCOPE_AGENT); }
; __device__ __forceinline__ unsigned xb_add(unsigned* p, unsigned v) { return __hip_atomic_fetch_add(p, v, __ATOMIC_RELAXED, __HIP_MEMORY_SCOPE_AGENT); }
; #define XB_SPIN(cond, bar) do { unsigned _sp = 0; while (cond) { __builtin_amdgcn_s_sleep(1); \
;     if ((++_sp & 255u) == 0u) { if (xb_ld(&(bar)[XB_TMO])) break; if (_sp > XB_SPIN_CAP) { atomicAdd(&(bar)[XB_TMO], 1u); break; } } } } while (0)
; __device__ __forceinline__ void xcd_barrier(const XcdBarrier& b) {
;     ...
;             const unsigned og = xb_add(&bar[XB_TOP], 1u);
;             const unsigned tg = og / nx;
;             if (og + 1u == (tg + 1u) * nx) xb_add(&bar[XB_TOPGEN], 1u);
;             else XB_SPIN(xb_ld(&bar[XB_TOPGEN]) == tg, bar);
;             __builtin_amdgcn_fence(__ATOMIC_ACQUIRE, "agent");
;             xb_add(&bar[XB_XGEN(b.x)], 1u);
;             asm volatile("s_waitcnt vmcnt(0)" ::: "memory");
;         } else {
;             XB_SPIN(xb_ld(&bar[XB_XGEN(b.x)]) == gen, bar);
;             __builtin_amdgcn_fence(__ATOMIC_ACQUIRE, "agent");
;             asm volatile("s_waitcnt vmcnt(0)" ::: "memory");
.LBB0_592:
	s_or_b64 exec, exec, s[14:15]
	s_mov_b64 s[14:15], exec
	v_mbcnt_lo_u32_b32 v0, s14, 0
	v_mbcnt_hi_u32_b32 v0, s15, v0
	v_cmp_eq_u32_e32 vcc, 0, v0
	s_waitcnt vmcnt(0)
	s_and_saveexec_b64 s[16:17], vcc
	s_cbranch_execz .LBB0_594
	s_bcnt1_i32_b64 s6, s[14:15]
	v_mov_b32_e32 v0, 0x2000
	v_mov_b32_e32 v1, s6
	global_atomic_add v0, v1, s[12:13] offset:1024

; __device__ __forceinline__ unsigned xb_ld(unsigned* p)              { return __hip_atomic_load(p, __ATOMIC_RELAXED, __HIP_MEMORY_SCOPE_AGENT); }
; __device__ __forceinline__ unsigned xb_add(unsigned* p, unsigned v) { return __hip_atomic_fetch_add(p, v, __ATOMIC_RELAXED, __HIP_MEMORY_SCOPE_AGENT); }
; #define XB_SPIN(cond, bar) do { unsigned _sp = 0; while (cond) { __builtin_amdgcn_s_sleep(1); \
;     if ((++_sp & 255u) == 0u) { if (xb_ld(&(bar)[XB_TMO])) break; if (_sp > XB_SPIN_CAP) { atomicAdd(&(bar)[XB_TMO], 1u); break; } } } } while (0)
; __device__ __forceinline__ void xcd_barrier(const XcdBarrier& b) {
;     ...
;             const unsigned og = xb_add(&bar[XB_TOP], 1u);
;             const unsigned tg = og / nx;
;             if (og + 1u == (tg + 1u) * nx) xb_add(&bar[XB_TOPGEN], 1u);
;             else XB_SPIN(xb_ld(&bar[XB_TOPGEN]) == tg, bar);
;             __builtin_amdgcn_fence(__ATOMIC_ACQUIRE, "agent");
;             xb_add(&bar[XB_XGEN(b.x)], 1u);
;             asm volatile("s_waitcnt vmcnt(0)" ::: "memory");
;         } else {
;             XB_SPIN(xb_ld(&bar[XB_XGEN(b.x)]) == gen, bar);
;             __builtin_amdgcn_fence(__ATOMIC_ACQUIRE, "agent");
;             asm volatile("s_waitcnt vmcnt(0)" ::: "memory");
.LBB0_2080:
	s_or_b64 exec, exec, s[10:11]
	s_mov_b64 s[10:11], exec
	v_mbcnt_lo_u32_b32 v0, s10, 0
	v_mbcnt_hi_u32_b32 v0, s11, v0
	v_cmp_eq_u32_e32 vcc, 0, v0
	s_waitcnt vmcnt(0)
	s_and_saveexec_b64 s[12:13], vcc
	s_cbranch_execz .LBB0_2082
	s_bcnt1_i32_b64 s10, s[10:11]
	v_mov_b32_e32 v0, 0x2000
	v_mov_b32_e32 v1, s10
	global_atomic_add v0, v1, s[8:9] offset:1024
.LBB0_2082:
	s_or_b64 exec, exec, s[12:13]
	buffer_inv sc1
	s_waitcnt vmcnt(0)

; __device__ __forceinline__ unsigned xb_ld(unsigned* p)              { return __hip_atomic_load(p, __ATOMIC_RELAXED, __HIP_MEMORY_SCOPE_AGENT); }
; __device__ __forceinline__ unsigned xb_add(unsigned* p, unsigned v) { return __hip_atomic_fetch_add(p, v, __ATOMIC_RELAXED, __HIP_MEMORY_SCOPE_AGENT); }
; #define XB_SPIN(cond, bar) do { unsigned _sp = 0; while (cond) { __builtin_amdgcn_s_sleep(1); \
;     if ((++_sp & 255u) == 0u) { if (xb_ld(&(bar)[XB_TMO])) break; if (_sp > XB_SPIN_CAP) { atomicAdd(&(bar)[XB_TMO], 1u); break; } } } } while (0)
; __device__ __forceinline__ void xcd_barrier(const XcdBarrier& b) {
;     ...
;             const unsigned og = xb_add(&bar[XB_TOP], 1u);
;             const unsigned tg = og / nx;
;             if (og + 1u == (tg + 1u) * nx) xb_add(&bar[XB_TOPGEN], 1u);
;             else XB_SPIN(xb_ld(&bar[XB_TOPGEN]) == tg, bar);
;             __builtin_amdgcn_fence(__ATOMIC_ACQUIRE, "agent");
;             xb_add(&bar[XB_XGEN(b.x)], 1u);
;             asm volatile("s_waitcnt vmcnt(0)" ::: "memory");
;         } else {
;             XB_SPIN(xb_ld(&bar[XB_XGEN(b.x)]) == gen, bar);
;             __builtin_amdgcn_fence(__ATOMIC_ACQUIRE, "agent");
;             asm volatile("s_waitcnt vmcnt(0)" ::: "memory");
.LBB0_2316:
	s_or_b64 exec, exec, s[8:9]
	s_mov_b64 s[8:9], exec
	v_mbcnt_lo_u32_b32 v0, s8, 0
	v_mbcnt_hi_u32_b32 v0, s9, v0
	v_cmp_eq_u32_e32 vcc, 0, v0
	s_waitcnt vmcnt(0)
	s_and_saveexec_b64 s[10:11], vcc
	s_cbranch_execz .LBB0_2318
	s_bcnt1_i32_b64 s3, s[8:9]
	v_mov_b32_e32 v0, 0x2000
	v_mov_b32_e32 v1, s3
	global_atomic_add v0, v1, s[4:5] offset:1024
.LBB0_2318:
	s_or_b64 exec, exec, s[10:11]
	buffer_inv sc1
	s_waitcnt vmcnt(0)
